# A-attn uniform tiles: softmax VALU interleaved between the QK/PV MFMAs (no setprio toggles)
# baseline (speedup 1.0000x reference)
; template <int DQK, int VAR> ...
;     ...
;         __builtin_amdgcn_sched_barrier(0);
;         __builtin_amdgcn_s_setprio(1);
; #pragma unroll
;         for (int c = 0; c < 2; ++c) {
;             s[0][ch * 2 + c] = (f32x4){sinit, sinit, sinit, sinit}; s[1][ch * 2 + c] = s[0][ch * 2 + c];
; #pragma unroll
;             for (int ks = 0; ks < DQK / 32; ++ks) {
;                 s[0][ch * 2 + c] = __builtin_amdgcn_mfma_f32_16x16x32_bf16(kfr[c][ks], qf[0][ks], s[0][ch * 2 + c], 0, 0, 0);
;                 s[1][ch * 2 + c] = __builtin_amdgcn_mfma_f32_16x16x32_bf16(kfr[c][ks], qf[1][ks], s[1][ch * 2 + c], 0, 0, 0);
;             }
;         }
;         __builtin_amdgcn_s_setprio(0);
;         __builtin_amdgcn_sched_barrier(0);
;     }
;     __builtin_amdgcn_s_setprio(0);
;     __builtin_amdgcn_sched_barrier(0);
; #pragma unroll
;     for (int kk = 0; kk < 2; ++kk)
; #pragma unroll
;         for (int dt = 0; dt < 4; ++dt) {
;             const LAS bf16_t* vp = sVt + (dt * 16 + lr) * VP + kk * 32 + lg * 4;
;             const u32x2 v0 = *(const LAS u32x2*)vp, v1 = *(const LAS u32x2*)(vp + 16);
;             vfr[kk][dt].x = v0.x; vfr[kk][dt].y = v0.y; vfr[kk][dt].z = v1.x; vfr[kk][dt].w = v1.y;
;         }
;     __builtin_amdgcn_sched_barrier(0);
; #pragma unroll
;     for (int qt = 0; qt < 2; ++qt) {
;         const int dq = qi + qt * 16 - key0 - lg * 4;
;         const LAS float* bp = sBias + (dq + 33);
;         float ps = 0.f;
; #pragma unroll
;         for (int c = 0; c < 4; ++c)
; #pragma unroll
;             for (int j = 0; j < 4; ++j) {
;                 float val = s[qt][c][j]; float pv;
;                 if (VAR == 0) pv = fexp2(val);
;                 else if (VAR == 1) { pv = fexp2(val); pv = (dq >= c * 16 + j) ? pv : 0.f; }
; template <int DQK, int MODE>
; __device__ __forceinline__ void attn_unit(LAS unsigned char* lds, const AttnArgs& a, const unsigned char* lut) {
;     ...
;             } else {
;                 const unsigned long long w0 = mwc0 >> (lg * 4), w1 = mwc1 >> (lg * 4);
;                 mlo[0] = (unsigned)w0; mhi[0] = (unsigned)(w0 >> 32); mlo[1] = (unsigned)w1; mhi[1] = (unsigned)(w1 >> 32);
;                 const int uni = __builtin_amdgcn_readfirstlane((int)sUni[wid * 132 + kt]);
;                 if (uni) { const float ub = sBias[96 + wq_min - key0]; attn_tile<DQK, 3>(sK, sVt, sBias, qf, o, lsum, qi, key0, 0, mlo, mhi, nb + ub, lr, lg); }
.LBB0_338:
	s_add_i32 s0, s14, 0
	v_mov_b32_e32 v66, s0
	ds_read_u8 v66, v66
	s_add_i32 s0, s15, 0
	v_mov_b32_e32 v67, s0
	ds_read_b32 v78, v67
	s_mulk_i32 s19, 0x6000
	v_lshrrev_b64 v[62:63], v60, v[62:63]
	v_lshrrev_b64 v[64:65], v54, v[64:65]
	s_add_i32 s0, s19, 0
	v_add3_u32 v68, s0, v159, v160
	v_add3_u32 v96, s0, v0, v160
	v_add_u32_e32 v147, 0x3800, v68
	v_add_u32_e32 v146, 0x4000, v68
	v_add_u32_e32 v145, 0x4800, v68
	v_add_u32_e32 v144, 0x5000, v68
	s_movk_i32 s0, 0xf0
	v_lshlrev_b32_e32 v69, 4, v62
	v_lshrrev_b32_e32 v70, 12, v62
	v_lshlrev_b32_e32 v71, 4, v63
	v_lshrrev_b32_e32 v72, 12, v63
	v_lshlrev_b32_e32 v73, 4, v64
	v_lshrrev_b32_e32 v74, 12, v64
	v_lshlrev_b32_e32 v75, 4, v65
	v_lshrrev_b32_e32 v76, 12, v65
	v_and_or_b32 v69, v69, s0, v162
	v_and_or_b32 v70, v70, s0, v162
	v_and_or_b32 v71, v71, s0, v162
	v_and_or_b32 v72, v72, s0, v162
	v_and_or_b32 v73, v73, s0, v162
	v_and_or_b32 v74, v74, s0, v162
	v_and_or_b32 v75, v75, s0, v162
	v_and_or_b32 v76, v76, s0, v162
	s_mov_b32 vcc_lo, 0x76543210
	s_mov_b32 vcc_hi, 0xfedcba98
	s_waitcnt lgkmcnt(0)
	v_readfirstlane_b32 s1, v66
	v_sub_f32_e32 v78, v78, v55
	s_nop 0
	s_cmp_lg_u32 s1, 0
	s_cselect_b64 s[36:37], -1, 0
	v_cndmask_b32_e64 v77, v56, v78, s[36:37]
	v_cndmask_b32_e32 v77, v164, v77, vcc
	ds_write_b32 v163, v77
	ds_read_b128 v[80:83], v69
	ds_read_b128 v[84:87], v73
	ds_read_b128 v[148:151], v96
	ds_read_b128 v[152:155], v96 offset:64
	ds_read_b128 v[88:91], v70
	ds_read_b128 v[200:203], v74
	ds_read_b128 v[166:169], v96 offset:2304
	ds_read_b128 v[170:173], v96 offset:2368
	ds_read_b128 v[98:101], v71
	ds_read_b128 v[102:105], v75
	ds_read_b128 v[106:109], v72
	ds_read_b128 v[110:113], v76
	s_cmp_eq_u32 s1, 0
	s_cbranch_scc1 .Lmy_a_nonuni
	s_waitcnt lgkmcnt(9)
	v_mfma_f32_16x16x32_bf16 v[80:83], v[148:151], v[26:29], v[80:83]
	v_mfma_f32_16x16x32_bf16 v[84:87], v[148:151], v[34:37], v[84:87]
	ds_read_b128 v[174:177], v96 offset:4608
	ds_read_b128 v[178:181], v96 offset:4672
	ds_read_b128 v[182:185], v96 offset:6912
	ds_read_b128 v[186:189], v96 offset:6976
	s_waitcnt lgkmcnt(12)
	v_mfma_f32_16x16x32_bf16 v[80:83], v[152:155], v[30:33], v[80:83]
	v_mfma_f32_16x16x32_bf16 v[84:87], v[152:155], v[38:41], v[84:87]
	s_waitcnt lgkmcnt(9)
	v_mfma_f32_16x16x32_bf16 v[88:91], v[166:169], v[26:29], v[88:91]
	v_mfma_f32_16x16x32_bf16 v[200:203], v[166:169], v[34:37], v[200:203]
	s_waitcnt lgkmcnt(8)
	v_mfma_f32_16x16x32_bf16 v[88:91], v[170:173], v[30:33], v[88:91]
	v_mfma_f32_16x16x32_bf16 v[200:203], v[170:173], v[38:41], v[200:203]
	ds_read2_b64 v[148:151], v147 offset1:4
	ds_read2_b64 v[152:155], v146 offset0:32 offset1:36
	ds_read2_b64 v[166:169], v145 offset0:64 offset1:68
	ds_read2_b64 v[170:173], v144 offset0:96 offset1:100
	s_waitcnt lgkmcnt(7)
	v_mfma_f32_16x16x32_bf16 v[98:101], v[174:177], v[26:29], v[98:101]
	v_exp_f32_e32 v63, v80
	v_exp_f32_e32 v62, v84
	v_exp_f32_e32 v65, v81
	v_exp_f32_e32 v64, v85
	v_mfma_f32_16x16x32_bf16 v[102:105], v[174:177], v[34:37], v[102:105]
	v_exp_f32_e32 v67, v82
	v_exp_f32_e32 v66, v86
	v_pk_add_f32 v[142:143], v[62:63], v[64:65]
	v_exp_f32_e32 v69, v83
	s_waitcnt lgkmcnt(6)
	v_mfma_f32_16x16x32_bf16 v[98:101], v[178:181], v[30:33], v[98:101]
	v_exp_f32_e32 v68, v87
	v_pk_add_f32 v[142:143], v[142:143], v[66:67]
	v_cvt_pk_bf16_f32 v80, v63, v65
	v_cvt_pk_bf16_f32 v84, v62, v64
	v_mfma_f32_16x16x32_bf16 v[102:105], v[178:181], v[38:41], v[102:105]
	v_pk_add_f32 v[142:143], v[142:143], v[68:69]
	v_cvt_pk_bf16_f32 v81, v67, v69
	v_cvt_pk_bf16_f32 v85, v66, v68
	v_exp_f32_e32 v71, v88
	s_waitcnt lgkmcnt(5)
	v_mfma_f32_16x16x32_bf16 v[106:109], v[182:185], v[26:29], v[106:109]
	v_exp_f32_e32 v70, v200
	v_exp_f32_e32 v73, v89
	v_exp_f32_e32 v72, v201
	v_exp_f32_e32 v75, v90
	v_mfma_f32_16x16x32_bf16 v[110:113], v[182:185], v[34:37], v[110:113]
	v_exp_f32_e32 v74, v202
	v_pk_add_f32 v[142:143], v[142:143], v[70:71]
	v_exp_f32_e32 v77, v91
	v_exp_f32_e32 v76, v203
	s_waitcnt lgkmcnt(4)
	v_mfma_f32_16x16x32_bf16 v[106:109], v[186:189], v[30:33], v[106:109]
	v_pk_add_f32 v[142:143], v[142:143], v[72:73]
	v_cvt_pk_bf16_f32 v82, v71, v73
	v_cvt_pk_bf16_f32 v86, v70, v72
	v_pk_add_f32 v[142:143], v[142:143], v[74:75]
	v_mfma_f32_16x16x32_bf16 v[110:113], v[186:189], v[38:41], v[110:113]
	v_cvt_pk_bf16_f32 v83, v75, v77
	v_cvt_pk_bf16_f32 v87, v74, v76
	v_pk_add_f32 v[142:143], v[142:143], v[76:77]
	ds_read2_b64 v[174:177], v147 offset0:8 offset1:12
	ds_read2_b64 v[178:181], v146 offset0:40 offset1:44
	ds_read2_b64 v[182:185], v145 offset0:72 offset1:76
	ds_read2_b64 v[186:189], v144 offset0:104 offset1:108
	s_waitcnt lgkmcnt(7)
	v_mfma_f32_16x16x32_bf16 v[50:53], v[148:151], v[80:83], v[50:53]
	v_exp_f32_e32 v219, v98
	v_exp_f32_e32 v218, v102
	v_exp_f32_e32 v221, v99
	v_exp_f32_e32 v220, v103
	v_mfma_f32_16x16x32_bf16 v[14:17], v[148:151], v[84:87], v[14:17]
	v_exp_f32_e32 v223, v100
	v_exp_f32_e32 v222, v104
	v_pk_add_f32 v[142:143], v[142:143], v[218:219]
	v_exp_f32_e32 v225, v101
	s_waitcnt lgkmcnt(6)
	v_mfma_f32_16x16x32_bf16 v[42:45], v[152:155], v[80:83], v[42:45]
	v_exp_f32_e32 v224, v105
	v_pk_add_f32 v[142:143], v[142:143], v[220:221]
	v_cvt_pk_bf16_f32 v88, v219, v221
	v_cvt_pk_bf16_f32 v200, v218, v220
	v_mfma_f32_16x16x32_bf16 v[10:13], v[152:155], v[84:87], v[10:13]
	v_pk_add_f32 v[142:143], v[142:143], v[222:223]
	v_cvt_pk_bf16_f32 v89, v223, v225
	v_cvt_pk_bf16_f32 v201, v222, v224
	v_pk_add_f32 v[142:143], v[142:143], v[224:225]
	s_waitcnt lgkmcnt(5)
	v_mfma_f32_16x16x32_bf16 v[22:25], v[166:169], v[80:83], v[22:25]
	v_exp_f32_e32 v231, v106
	v_exp_f32_e32 v230, v110
	v_exp_f32_e32 v233, v107
	v_exp_f32_e32 v232, v111
	v_mfma_f32_16x16x32_bf16 v[6:9], v[166:169], v[84:87], v[6:9]
	v_exp_f32_e32 v235, v108
	v_exp_f32_e32 v234, v112
	v_pk_add_f32 v[142:143], v[142:143], v[230:231]
	v_exp_f32_e32 v237, v109
	s_waitcnt lgkmcnt(4)
	v_mfma_f32_16x16x32_bf16 v[18:21], v[170:173], v[80:83], v[18:21]
	v_exp_f32_e32 v236, v113
	v_pk_add_f32 v[142:143], v[142:143], v[232:233]
	v_cvt_pk_bf16_f32 v90, v231, v233
	v_cvt_pk_bf16_f32 v202, v230, v232
	v_mfma_f32_16x16x32_bf16 v[2:5], v[170:173], v[84:87], v[2:5]
	v_pk_add_f32 v[142:143], v[142:143], v[234:235]
	v_cvt_pk_bf16_f32 v91, v235, v237
	v_cvt_pk_bf16_f32 v203, v234, v236
	v_pk_add_f32 v[142:143], v[142:143], v[236:237]
	s_waitcnt lgkmcnt(3)
	v_mfma_f32_16x16x32_bf16 v[50:53], v[174:177], v[88:91], v[50:53]
	v_mfma_f32_16x16x32_bf16 v[14:17], v[174:177], v[200:203], v[14:17]
	s_waitcnt lgkmcnt(2)
	v_mfma_f32_16x16x32_bf16 v[42:45], v[178:181], v[88:91], v[42:45]
	v_mfma_f32_16x16x32_bf16 v[10:13], v[178:181], v[200:203], v[10:13]
	s_waitcnt lgkmcnt(1)
	v_mfma_f32_16x16x32_bf16 v[22:25], v[182:185], v[88:91], v[22:25]
	v_mfma_f32_16x16x32_bf16 v[6:9], v[182:185], v[200:203], v[6:9]
	s_waitcnt lgkmcnt(0)
	v_mfma_f32_16x16x32_bf16 v[18:21], v[186:189], v[88:91], v[18:21]
	v_mfma_f32_16x16x32_bf16 v[2:5], v[186:189], v[200:203], v[2:5]
	s_branch .LBB0_341
; template <int DQK, int VAR> ...
;     ...
;         __builtin_amdgcn_sched_barrier(0);
;         __builtin_amdgcn_s_setprio(1);
; #pragma unroll
;         for (int c = 0; c < 2; ++c) {
;             s[0][ch * 2 + c] = (f32x4){sinit, sinit, sinit, sinit}; s[1][ch * 2 + c] = s[0][ch * 2 + c];
; #pragma unroll
;             for (int ks = 0; ks < DQK / 32; ++ks) {
;                 s[0][ch * 2 + c] = __builtin_amdgcn_mfma_f32_16x16x32_bf16(kfr[c][ks], qf[0][ks], s[0][ch * 2 + c], 0, 0, 0);
;                 s[1][ch * 2 + c] = __builtin_amdgcn_mfma_f32_16x16x32_bf16(kfr[c][ks], qf[1][ks], s[1][ch * 2 + c], 0, 0, 0);
;             }
;         }
;         __builtin_amdgcn_s_setprio(0);
;         __builtin_amdgcn_sched_barrier(0);
;     }
;     __builtin_amdgcn_s_setprio(0);
;     __builtin_amdgcn_sched_barrier(0);
; #pragma unroll
;     for (int kk = 0; kk < 2; ++kk)
; #pragma unroll
;         for (int dt = 0; dt < 4; ++dt) {
;             const LAS bf16_t* vp = sVt + (dt * 16 + lr) * VP + kk * 32 + lg * 4;
;             const u32x2 v0 = *(const LAS u32x2*)vp, v1 = *(const LAS u32x2*)(vp + 16);
;             vfr[kk][dt].x = v0.x; vfr[kk][dt].y = v0.y; vfr[kk][dt].z = v1.x; vfr[kk][dt].w = v1.y;
;         }
;     __builtin_amdgcn_sched_barrier(0);
; #pragma unroll
;     for (int qt = 0; qt < 2; ++qt) {
;         const int dq = qi + qt * 16 - key0 - lg * 4;
;         const LAS float* bp = sBias + (dq + 33);
;         float ps = 0.f;
; #pragma unroll
;         for (int c = 0; c < 4; ++c)
; #pragma unroll
;             for (int j = 0; j < 4; ++j) {
;                 float val = s[qt][c][j]; float pv;
;                 if (VAR == 0) pv = fexp2(val);
;                 else if (VAR == 1) { pv = fexp2(val); pv = (dq >= c * 16 + j) ? pv : 0.f; }
;                 else if (VAR == 2) { pv = fexp2(val + bp[63 - (c * 16 + j)]); }
;                 else if (VAR == 3) { pv = fexp2(val); pv = __uint_as_float(__float_as_uint(pv) & (unsigned)__builtin_amdgcn_sbfe((int)(c < 2 ? mlo[qt] : mhi[qt]), (c & 1) * 16 + j, 1)); }
;                 else { pv = fexp2(val + bp[63 - (c * 16 + j)]); pv = __uint_as_float(__float_as_uint(pv) & (unsigned)__builtin_amdgcn_sbfe((int)(c < 2 ? mlo[qt] : mhi[qt]), (c & 1) * 16 + j, 1)); }
;                 s[qt][c][j] = pv; ps += pv;
;             }
;         lsum[qt] += ps;
;     }
;     __builtin_amdgcn_s_setprio(1);
; #pragma unroll
.Lmy_a_nonuni:
	s_setprio 1
	s_waitcnt lgkmcnt(9)
	v_mfma_f32_16x16x32_bf16 v[80:83], v[148:151], v[26:29], v[80:83]
	v_mfma_f32_16x16x32_bf16 v[84:87], v[148:151], v[34:37], v[84:87]
	ds_read_b128 v[174:177], v96 offset:4608
	ds_read_b128 v[178:181], v96 offset:4672
	ds_read_b128 v[182:185], v96 offset:6912
	ds_read_b128 v[186:189], v96 offset:6976
	s_waitcnt lgkmcnt(12)
	v_mfma_f32_16x16x32_bf16 v[80:83], v[152:155], v[30:33], v[80:83]
	v_mfma_f32_16x16x32_bf16 v[84:87], v[152:155], v[38:41], v[84:87]
	s_waitcnt lgkmcnt(9)
	v_mfma_f32_16x16x32_bf16 v[88:91], v[166:169], v[26:29], v[88:91]
	v_mfma_f32_16x16x32_bf16 v[200:203], v[166:169], v[34:37], v[200:203]
	s_waitcnt lgkmcnt(8)
	v_mfma_f32_16x16x32_bf16 v[88:91], v[170:173], v[30:33], v[88:91]
	v_mfma_f32_16x16x32_bf16 v[200:203], v[170:173], v[38:41], v[200:203]
	s_waitcnt lgkmcnt(3)
	v_mfma_f32_16x16x32_bf16 v[98:101], v[174:177], v[26:29], v[98:101]
	v_mfma_f32_16x16x32_bf16 v[102:105], v[174:177], v[34:37], v[102:105]
	s_waitcnt lgkmcnt(2)
	v_mfma_f32_16x16x32_bf16 v[98:101], v[178:181], v[30:33], v[98:101]
	v_mfma_f32_16x16x32_bf16 v[102:105], v[178:181], v[38:41], v[102:105]
	s_waitcnt lgkmcnt(1)
	v_mfma_f32_16x16x32_bf16 v[106:109], v[182:185], v[26:29], v[106:109]
	v_mfma_f32_16x16x32_bf16 v[110:113], v[182:185], v[34:37], v[110:113]
	s_waitcnt lgkmcnt(0)
	v_mfma_f32_16x16x32_bf16 v[106:109], v[186:189], v[30:33], v[106:109]
	v_mfma_f32_16x16x32_bf16 v[110:113], v[186:189], v[38:41], v[110:113]
	s_setprio 0
	v_add_u32_e32 v165, 0x13cb4, v123
	ds_read2_b32 v[78:79], v165 offset0:66 offset1:67
	ds_read2_b32 v[190:191], v165 offset0:64 offset1:65
	ds_read2_b32 v[136:137], v165 offset0:50 offset1:51
	ds_read2_b32 v[214:215], v165 offset0:48 offset1:49
	ds_read2_b32 v[238:239], v165 offset0:34 offset1:35
	ds_read2_b32 v[92:93], v165 offset0:32 offset1:33
	ds_read2_b32 v[218:219], v165 offset0:18 offset1:19
	ds_read2_b32 v[220:221], v165 offset0:16 offset1:17
	ds_read2_b32 v[222:223], v165 offset0:2 offset1:3
	ds_read2_b32 v[224:225], v165 offset1:1
	ds_read2_b64 v[148:151], v147 offset1:4
	ds_read2_b64 v[152:155], v146 offset0:32 offset1:36
	ds_read2_b64 v[166:169], v145 offset0:64 offset1:68
	ds_read2_b64 v[170:173], v144 offset0:96 offset1:100
	s_waitcnt lgkmcnt(12)
	v_add_f32_e32 v84, v84, v79
	v_add_f32_e32 v85, v85, v78
	v_add_f32_e32 v86, v86, v191
	v_add_f32_e32 v87, v87, v190
	ds_read2_b64 v[174:177], v147 offset0:8 offset1:12
	ds_read2_b64 v[178:181], v146 offset0:40 offset1:44
	s_waitcnt lgkmcnt(12)
	v_add_f32_e32 v80, v80, v137
	v_add_f32_e32 v81, v81, v136
	v_add_f32_e32 v82, v82, v215
	v_add_f32_e32 v83, v83, v214
	v_add_f32_e32 v200, v200, v137
	v_add_f32_e32 v201, v201, v136
	v_add_f32_e32 v202, v202, v215
	v_add_f32_e32 v203, v203, v214
	ds_read2_b64 v[182:185], v145 offset0:72 offset1:76
	ds_read2_b64 v[186:189], v144 offset0:104 offset1:108
	s_waitcnt lgkmcnt(12)
	v_add_f32_e32 v88, v88, v239
	v_add_f32_e32 v89, v89, v238
	v_add_f32_e32 v90, v90, v93
	v_add_f32_e32 v91, v91, v92
	v_add_f32_e32 v102, v102, v239
	v_add_f32_e32 v103, v103, v238
	v_add_f32_e32 v104, v104, v93
	v_add_f32_e32 v105, v105, v92
	s_waitcnt lgkmcnt(10)
	v_add_f32_e32 v98, v98, v219
	v_add_f32_e32 v99, v99, v218
	v_add_f32_e32 v100, v100, v221
	v_add_f32_e32 v101, v101, v220
	v_add_f32_e32 v110, v110, v219
	v_add_f32_e32 v111, v111, v218
	v_add_f32_e32 v112, v112, v221
	v_add_f32_e32 v113, v113, v220
	s_waitcnt lgkmcnt(8)
	v_add_f32_e32 v106, v106, v223
	v_add_f32_e32 v107, v107, v222
	v_add_f32_e32 v108, v108, v225
	v_add_f32_e32 v109, v109, v224
	v_exp_f32_e32 v63, v80
	v_exp_f32_e32 v62, v84
	v_exp_f32_e32 v65, v81
	v_exp_f32_e32 v64, v85
	v_exp_f32_e32 v67, v82
	v_exp_f32_e32 v66, v86
	v_pk_add_f32 v[142:143], v[62:63], v[64:65]
	v_exp_f32_e32 v69, v83
	v_exp_f32_e32 v68, v87
	v_pk_add_f32 v[142:143], v[142:143], v[66:67]
	v_cvt_pk_bf16_f32 v80, v63, v65
	v_cvt_pk_bf16_f32 v84, v62, v64
	v_pk_add_f32 v[142:143], v[142:143], v[68:69]
	v_cvt_pk_bf16_f32 v81, v67, v69
	v_cvt_pk_bf16_f32 v85, v66, v68
	v_exp_f32_e32 v71, v88
	v_exp_f32_e32 v70, v200
	v_exp_f32_e32 v73, v89
	v_exp_f32_e32 v72, v201
	v_exp_f32_e32 v75, v90
	v_exp_f32_e32 v74, v202
	v_pk_add_f32 v[142:143], v[142:143], v[70:71]
	v_exp_f32_e32 v77, v91
	v_exp_f32_e32 v76, v203
	v_pk_add_f32 v[142:143], v[142:143], v[72:73]
	v_cvt_pk_bf16_f32 v82, v71, v73
	v_cvt_pk_bf16_f32 v86, v70, v72
	v_pk_add_f32 v[142:143], v[142:143], v[74:75]
	v_cvt_pk_bf16_f32 v83, v75, v77
	v_cvt_pk_bf16_f32 v87, v74, v76
	v_pk_add_f32 v[142:143], v[142:143], v[76:77]
	v_exp_f32_e32 v219, v98
	v_exp_f32_e32 v218, v102
	v_exp_f32_e32 v221, v99
	v_exp_f32_e32 v220, v103
	v_exp_f32_e32 v223, v100
	v_exp_f32_e32 v222, v104
	v_pk_add_f32 v[142:143], v[142:143], v[218:219]
	v_exp_f32_e32 v225, v101
	v_exp_f32_e32 v224, v105
	v_pk_add_f32 v[142:143], v[142:143], v[220:221]
	v_cvt_pk_bf16_f32 v88, v219, v221
	v_cvt_pk_bf16_f32 v200, v218, v220
	v_pk_add_f32 v[142:143], v[142:143], v[222:223]
	v_cvt_pk_bf16_f32 v89, v223, v225
	v_cvt_pk_bf16_f32 v201, v222, v224
	v_pk_add_f32 v[142:143], v[142:143], v[224:225]
	v_exp_f32_e32 v231, v106
	v_exp_f32_e32 v230, v110
	v_exp_f32_e32 v233, v107
	v_exp_f32_e32 v232, v111
	v_exp_f32_e32 v235, v108
	v_exp_f32_e32 v234, v112
	v_pk_add_f32 v[142:143], v[142:143], v[230:231]
	v_exp_f32_e32 v237, v109
	v_exp_f32_e32 v236, v113
	v_pk_add_f32 v[142:143], v[142:143], v[232:233]
	v_cvt_pk_bf16_f32 v90, v231, v233
	v_cvt_pk_bf16_f32 v202, v230, v232
	v_pk_add_f32 v[142:143], v[142:143], v[234:235]
	v_cvt_pk_bf16_f32 v91, v235, v237
	v_cvt_pk_bf16_f32 v203, v234, v236
	v_pk_add_f32 v[142:143], v[142:143], v[236:237]
	s_setprio 1
	s_nop 0
	s_waitcnt lgkmcnt(7)
	v_mfma_f32_16x16x32_bf16 v[50:53], v[148:151], v[80:83], v[50:53]
	v_mfma_f32_16x16x32_bf16 v[14:17], v[148:151], v[84:87], v[14:17]
	s_waitcnt lgkmcnt(6)
	v_mfma_f32_16x16x32_bf16 v[42:45], v[152:155], v[80:83], v[42:45]
	v_mfma_f32_16x16x32_bf16 v[10:13], v[152:155], v[84:87], v[10:13]
	s_waitcnt lgkmcnt(5)
	v_mfma_f32_16x16x32_bf16 v[22:25], v[166:169], v[80:83], v[22:25]
	v_mfma_f32_16x16x32_bf16 v[6:9], v[166:169], v[84:87], v[6:9]
	s_waitcnt lgkmcnt(4)
	v_mfma_f32_16x16x32_bf16 v[18:21], v[170:173], v[80:83], v[18:21]
	v_mfma_f32_16x16x32_bf16 v[2:5], v[170:173], v[84:87], v[2:5]
	s_waitcnt lgkmcnt(3)
	v_mfma_f32_16x16x32_bf16 v[50:53], v[174:177], v[88:91], v[50:53]
	v_mfma_f32_16x16x32_bf16 v[14:17], v[174:177], v[200:203], v[14:17]
	s_waitcnt lgkmcnt(2)
	v_mfma_f32_16x16x32_bf16 v[42:45], v[178:181], v[88:91], v[42:45]
	v_mfma_f32_16x16x32_bf16 v[10:13], v[178:181], v[200:203], v[10:13]
	s_waitcnt lgkmcnt(1)
	v_mfma_f32_16x16x32_bf16 v[22:25], v[182:185], v[88:91], v[22:25]
	v_mfma_f32_16x16x32_bf16 v[6:9], v[182:185], v[200:203], v[6:9]
	s_waitcnt lgkmcnt(0)
	v_mfma_f32_16x16x32_bf16 v[18:21], v[186:189], v[88:91], v[18:21]
	v_mfma_f32_16x16x32_bf16 v[2:5], v[186:189], v[200:203], v[2:5]
